# v35 plus FFN-up epilogue halo (HZ) stores compacted: 8 four-lane stores per wave become one 32-lane store via DPP row shifts
# baseline (speedup 1.0000x reference)
; #define PG8_LAS __attribute__((address_space(3)))
; __device__ __forceinline__ float rstd2048(const stat_t* rs, int row) { return rsqrtf((float)rs[row] * (STAT_INV / 2048.0f) + NORM_EPS); }
;     __device__ __forceinline__ void operator()(const f32x4 (&acc)[2][2][4][2], const Unit& u, int wr, int wc, int fr_, int fq_) const {
;     ...
;             for (int m = 0; m < 4; ++m) { const float r = rstd2048(rs, rowb + ai * HALF + m) * sx[rowb + ai * HALF + m];
; #pragma unroll
;                 for (int bj = 0; bj < 2; ++bj)
; #pragma unroll
;                     for (int n = 0; n < 2; ++n) { typedef int i32x4 __attribute__((ext_vector_type(4)));
;                         z[ai][bj][m][n] = __builtin_convertvector(__builtin_bit_cast(i32x4, acc[ai][bj][m][n]), f32x4) * (swv[bj][n] * r); } }
;         PG8_LAS f32x4* X4 = (PG8_LAS f32x4*)xch;
;     ...
; #pragma unroll
;         for (int ai = 0; ai < 2; ++ai) {
;             if (fr == 0) {
; #pragma unroll
;                 for (int bj = 0; bj < 2; ++bj)
; #pragma unroll
;                     for (int n = 0; n < 2; ++n) X4[XIDX(wr, ai, 0) + bj * 2 + n] = z[ai][bj][0][n]; }
;             if (fr == 15) {
; #pragma unroll
;                 for (int bj = 0; bj < 2; ++bj)
; #pragma unroll
;                     for (int n = 0; n < 2; ++n) X4[XIDX(wr, ai, 1) + bj * 2 + n] = z[ai][bj][3][n]; }
;         }
;         {   const int hcol = u.pn * BM + wc * 32 + 8 * fq;
;             if (wr == 0 && fr == 0) {
; #pragma unroll
;                 for (int m = 0; m < 2; ++m)
; #pragma unroll
;                     for (int bj = 0; bj < 2; ++bj)
; #pragma unroll
;                         for (int n = 0; n < 2; ++n) *(f32x4*)(HZ + (size_t)(u.pm * 4 + m) * NZ_ + hcol + bj * HALF + 4 * n) = z[0][bj][m][n]; }
.LBB0_97:
	s_or_b64 exec, exec, s[0:1]
	v_ffbh_u32_e32 v78, v167
	v_min_u32_e32 v94, 32, v78
	v_lshlrev_b64 v[78:79], v94, v[166:167]
	v_min_u32_e32 v78, 1, v78
	v_or_b32_e32 v78, v79, v78
	v_cvt_f32_u32_e32 v78, v78
	v_sub_u32_e32 v94, 32, v94
	v_cvt_f32_i32_e32 v79, v119
	v_cvt_f32_i32_e32 v119, v121
	v_ldexp_f32 v78, v78, v94
	v_fmamk_f32 v78, v78, 0x2e000000, v204
	v_mul_f32_e32 v94, 0x4b800000, v78
	v_cmp_gt_f32_e32 vcc, s17, v78
	v_cvt_f32_i32_e32 v113, v113
	v_cvt_f32_i32_e32 v112, v112
	v_cndmask_b32_e32 v78, v78, v94, vcc
	v_rsq_f32_e32 v94, v78
	v_cvt_f32_i32_e32 v78, v118
	v_cvt_f32_i32_e32 v118, v120
	v_cvt_f32_i32_e32 v105, v105
	v_mul_f32_e32 v97, 0x45800000, v94
	v_cndmask_b32_e32 v94, v94, v97, vcc
	v_mul_f32_e32 v94, v159, v94
	v_pk_mul_f32 v[156:157], v[38:39], v[94:95] op_sel_hi:[1,0]
	v_pk_mul_f32 v[120:121], v[40:41], v[94:95] op_sel_hi:[1,0]
	v_cvt_f32_i32_e32 v104, v104
	v_pk_mul_f32 v[120:121], v[120:121], v[118:119]
	v_pk_mul_f32 v[118:119], v[156:157], v[78:79]
	v_cvt_f32_i32_e32 v79, v111
	v_cvt_f32_i32_e32 v78, v110
	v_pk_mul_f32 v[110:111], v[18:19], v[94:95] op_sel_hi:[1,0]
	v_pk_mul_f32 v[156:157], v[20:21], v[94:95] op_sel_hi:[1,0]
	v_cvt_f32_i32_e32 v101, v101
	v_pk_mul_f32 v[110:111], v[110:111], v[78:79]
	v_cvt_f32_i32_e32 v79, v103
	v_cvt_f32_i32_e32 v78, v102
	v_pk_mul_f32 v[112:113], v[156:157], v[112:113]
	v_pk_mul_f32 v[102:103], v[34:35], v[94:95] op_sel_hi:[1,0]
	v_pk_mul_f32 v[156:157], v[36:37], v[94:95] op_sel_hi:[1,0]
	v_cvt_f32_i32_e32 v100, v100
	v_pk_mul_f32 v[158:159], v[156:157], v[104:105]
	v_pk_mul_f32 v[156:157], v[102:103], v[78:79]
	v_cvt_f32_i32_e32 v79, v99
	v_cvt_f32_i32_e32 v78, v98
	v_pk_mul_f32 v[98:99], v[22:23], v[94:95] op_sel_hi:[1,0]
	s_or_b32 s0, s66, s36
	v_pk_mul_f32 v[102:103], v[24:25], v[94:95] op_sel_hi:[1,0]
	v_pk_mul_f32 v[98:99], v[98:99], v[78:79]
	v_add_u32_e32 v78, s0, v168
	v_readlane_b32 s0, v254, 58
	v_pk_mul_f32 v[100:101], v[102:103], v[100:101]
	s_nop 0
	v_or_b32_e32 v79, s0, v174
	v_cmp_eq_u32_e32 vcc, 0, v79
	v_ashrrev_i32_e32 v79, 31, v78
	v_readlane_b32 s4, v254, 58
	s_nop 3
	s_cmp_lg_u32 s4, 0
	s_cbranch_scc1 .LBB0_99
	v_mov_b32_e32 v176, v150
	v_mov_b32_e32 v177, v151
	v_mov_b32_e32 v178, v152
	v_mov_b32_e32 v179, v153
	v_mov_b32_dpp v176, v146 row_shr:1 row_mask:0xf bank_mask:0xf
	v_mov_b32_dpp v177, v147 row_shr:1 row_mask:0xf bank_mask:0xf
	v_mov_b32_dpp v178, v148 row_shr:1 row_mask:0xf bank_mask:0xf
	v_mov_b32_dpp v179, v149 row_shr:1 row_mask:0xf bank_mask:0xf
	v_mov_b32_dpp v176, v142 row_shr:2 row_mask:0xf bank_mask:0xf
	v_mov_b32_dpp v177, v143 row_shr:2 row_mask:0xf bank_mask:0xf
	v_mov_b32_dpp v178, v144 row_shr:2 row_mask:0xf bank_mask:0xf
	v_mov_b32_dpp v179, v145 row_shr:2 row_mask:0xf bank_mask:0xf
	v_mov_b32_dpp v176, v138 row_shr:3 row_mask:0xf bank_mask:0xf
	v_mov_b32_dpp v177, v139 row_shr:3 row_mask:0xf bank_mask:0xf
	v_mov_b32_dpp v178, v140 row_shr:3 row_mask:0xf bank_mask:0xf
	v_mov_b32_dpp v179, v141 row_shr:3 row_mask:0xf bank_mask:0xf
	v_mov_b32_dpp v176, v118 row_shr:4 row_mask:0xf bank_mask:0xf
	v_mov_b32_dpp v177, v119 row_shr:4 row_mask:0xf bank_mask:0xf
	v_mov_b32_dpp v178, v120 row_shr:4 row_mask:0xf bank_mask:0xf
	v_mov_b32_dpp v179, v121 row_shr:4 row_mask:0xf bank_mask:0xf
	v_mov_b32_dpp v176, v110 row_shr:5 row_mask:0xf bank_mask:0xf
	v_mov_b32_dpp v177, v111 row_shr:5 row_mask:0xf bank_mask:0xf
	v_mov_b32_dpp v178, v112 row_shr:5 row_mask:0xf bank_mask:0xf
	v_mov_b32_dpp v179, v113 row_shr:5 row_mask:0xf bank_mask:0xf
	v_mov_b32_dpp v176, v156 row_shr:6 row_mask:0xf bank_mask:0xf
	v_mov_b32_dpp v177, v157 row_shr:6 row_mask:0xf bank_mask:0xf
	v_mov_b32_dpp v178, v158 row_shr:6 row_mask:0xf bank_mask:0xf
	v_mov_b32_dpp v179, v159 row_shr:6 row_mask:0xf bank_mask:0xf
	v_mov_b32_dpp v176, v98 row_shr:7 row_mask:0xf bank_mask:0xf
	v_mov_b32_dpp v177, v99 row_shr:7 row_mask:0xf bank_mask:0xf
	v_mov_b32_dpp v178, v100 row_shr:7 row_mask:0xf bank_mask:0xf
	v_mov_b32_dpp v179, v101 row_shr:7 row_mask:0xf bank_mask:0xf
	v_and_b32_e32 v182, 1, v174
	v_lshlrev_b32_e32 v182, 4, v182
	v_bfe_u32 v183, v174, 1, 1
	v_lshl_or_b32 v182, v183, 9, v182
	v_bfe_u32 v183, v174, 2, 1
	v_mul_u32_u24_e32 v183, 0xb000, v183
	v_add_u32_e32 v182, v182, v183
	v_cmp_gt_u32_e32 vcc, 8, v174
	s_and_saveexec_b64 s[0:1], vcc
	s_cbranch_execz .LBB0_99
	s_lshl_b32 s4, s10, 2
	s_mul_i32 s5, s10, 0x2c000
	v_readlane_b32 s8, v252, 43
	s_mul_hi_i32 s7, s4, 0xb000
	v_readlane_b32 s9, v252, 44
	s_nop 1
	s_add_u32 s6, s8, s5
	s_addc_u32 s7, s9, s7
	v_lshlrev_b64 v[102:103], 2, v[78:79]
	v_lshl_add_u64 v[180:181], s[6:7], 0, v[102:103]
	v_add_co_u32_e32 v180, vcc, v180, v182
	s_nop 1
	v_addc_co_u32_e32 v181, vcc, 0, v181, vcc
	global_store_dwordx4 v[180:181], v[176:179], off
; #define PG8_LAS __attribute__((address_space(3)))
; __device__ __forceinline__ float rstd2048(const stat_t* rs, int row) { return rsqrtf((float)rs[row] * (STAT_INV / 2048.0f) + NORM_EPS); }
;     __device__ __forceinline__ void operator()(const f32x4 (&acc)[2][2][4][2], const Unit& u, int wr, int wc, int fr_, int fq_) const {
;     ...
;             for (int m = 0; m < 4; ++m) { const float r = rstd2048(rs, rowb + ai * HALF + m) * sx[rowb + ai * HALF + m];
; #pragma unroll
;                 for (int bj = 0; bj < 2; ++bj)
; #pragma unroll
;                     for (int n = 0; n < 2; ++n) { typedef int i32x4 __attribute__((ext_vector_type(4)));
;                         z[ai][bj][m][n] = __builtin_convertvector(__builtin_bit_cast(i32x4, acc[ai][bj][m][n]), f32x4) * (swv[bj][n] * r); } }
;         PG8_LAS f32x4* X4 = (PG8_LAS f32x4*)xch;
;     ...
; #pragma unroll
;         for (int ai = 0; ai < 2; ++ai) {
;             if (fr == 0) {
; #pragma unroll
;                 for (int bj = 0; bj < 2; ++bj)
; #pragma unroll
;                     for (int n = 0; n < 2; ++n) X4[XIDX(wr, ai, 0) + bj * 2 + n] = z[ai][bj][0][n]; }
;             if (fr == 15) {
; #pragma unroll
;                 for (int bj = 0; bj < 2; ++bj)
; #pragma unroll
;                     for (int n = 0; n < 2; ++n) X4[XIDX(wr, ai, 1) + bj * 2 + n] = z[ai][bj][3][n]; }
;         }
;         {   const int hcol = u.pn * BM + wc * 32 + 8 * fq;
;             if (wr == 0 && fr == 0) {
; #pragma unroll
;                 for (int m = 0; m < 2; ++m)
; #pragma unroll
;                     for (int bj = 0; bj < 2; ++bj)
; #pragma unroll
;                         for (int n = 0; n < 2; ++n) *(f32x4*)(HZ + (size_t)(u.pm * 4 + m) * NZ_ + hcol + bj * HALF + 4 * n) = z[0][bj][m][n]; }
;             if (wr == 1 && fr == 15) {
; #pragma unroll
;                 for (int m = 2; m < 4; ++m)
; #pragma unroll
;                     for (int bj = 0; bj < 2; ++bj)
; #pragma unroll
;                         for (int n = 0; n < 2; ++n) *(f32x4*)(HZ + (size_t)(u.pm * 4 + m) * NZ_ + hcol + bj * HALF + 4 * n) = z[1][bj][m][n]; }
.LBB0_99:
	s_or_b64 exec, exec, s[0:1]
	v_ffbh_u32_e32 v94, v163
	v_min_u32_e32 v94, 32, v94
	v_lshlrev_b64 v[102:103], v94, v[162:163]
	v_min_u32_e32 v97, 1, v102
	v_or_b32_e32 v97, v103, v97
	v_cvt_f32_u32_e32 v97, v97
	v_sub_u32_e32 v94, 32, v94
	v_cvt_f32_i32_e32 v91, v91
	v_cvt_f32_i32_e32 v90, v90
	v_ldexp_f32 v94, v97, v94
	v_fmamk_f32 v94, v94, 0x2e000000, v204
	v_mul_f32_e32 v97, 0x4b800000, v94
	v_cmp_gt_f32_e32 vcc, s17, v94
	v_cvt_f32_i32_e32 v93, v93
	v_cvt_f32_i32_e32 v92, v92
	v_cndmask_b32_e32 v94, v94, v97, vcc
	v_rsq_f32_e32 v94, v94
	v_cvt_f32_i32_e32 v87, v87
	v_cvt_f32_i32_e32 v89, v89
	v_cvt_f32_i32_e32 v88, v88
	v_mul_f32_e32 v97, 0x45800000, v94
	v_cndmask_b32_e32 v94, v94, v97, vcc
	v_cvt_f32_i32_e32 v86, v86
	v_mul_f32_e32 v94, v96, v94
	v_cvt_f32_i32_e32 v83, v83
	v_cvt_f32_i32_e32 v85, v85
	v_cvt_f32_i32_e32 v84, v84
	v_cvt_f32_i32_e32 v82, v82
	v_pk_mul_f32 v[96:97], v[38:39], v[94:95] op_sel_hi:[1,0]
	v_pk_mul_f32 v[102:103], v[40:41], v[94:95] op_sel_hi:[1,0]
	v_cvt_f32_i32_e32 v75, v75
	v_cvt_f32_i32_e32 v77, v77
	v_cvt_f32_i32_e32 v76, v76
	v_cvt_f32_i32_e32 v74, v74
	v_pk_mul_f32 v[92:93], v[102:103], v[92:93]
	v_pk_mul_f32 v[90:91], v[96:97], v[90:91]
	v_pk_mul_f32 v[96:97], v[18:19], v[94:95] op_sel_hi:[1,0]
	v_pk_mul_f32 v[102:103], v[20:21], v[94:95] op_sel_hi:[1,0]
	v_pk_mul_f32 v[86:87], v[96:97], v[86:87]
	v_pk_mul_f32 v[88:89], v[102:103], v[88:89]
	v_pk_mul_f32 v[96:97], v[34:35], v[94:95] op_sel_hi:[1,0]
	v_pk_mul_f32 v[102:103], v[36:37], v[94:95] op_sel_hi:[1,0]
	v_pk_mul_f32 v[82:83], v[96:97], v[82:83]
	v_pk_mul_f32 v[84:85], v[102:103], v[84:85]
	v_pk_mul_f32 v[96:97], v[22:23], v[94:95] op_sel_hi:[1,0]
	v_pk_mul_f32 v[102:103], v[24:25], v[94:95] op_sel_hi:[1,0]
	v_cmp_eq_u32_e32 vcc, 15, v174
	v_pk_mul_f32 v[76:77], v[102:103], v[76:77]
	v_pk_mul_f32 v[74:75], v[96:97], v[74:75]
	s_and_b64 s[6:7], s[46:47], vcc
	s_mov_b32 s12, s38
	v_readlane_b32 s4, v254, 58
	s_nop 3
	s_cmp_lg_u32 s4, 1
	s_cbranch_scc1 .LBB0_101
	v_mov_b32_e32 v176, v90
	v_mov_b32_e32 v177, v91
	v_mov_b32_e32 v178, v92
	v_mov_b32_e32 v179, v93
	v_mov_b32_dpp v176, v86 row_shl:1 row_mask:0xf bank_mask:0xf
	v_mov_b32_dpp v177, v87 row_shl:1 row_mask:0xf bank_mask:0xf
	v_mov_b32_dpp v178, v88 row_shl:1 row_mask:0xf bank_mask:0xf
	v_mov_b32_dpp v179, v89 row_shl:1 row_mask:0xf bank_mask:0xf
	v_mov_b32_dpp v176, v82 row_shl:2 row_mask:0xf bank_mask:0xf
	v_mov_b32_dpp v177, v83 row_shl:2 row_mask:0xf bank_mask:0xf
	v_mov_b32_dpp v178, v84 row_shl:2 row_mask:0xf bank_mask:0xf
	v_mov_b32_dpp v179, v85 row_shl:2 row_mask:0xf bank_mask:0xf
	v_mov_b32_dpp v176, v74 row_shl:3 row_mask:0xf bank_mask:0xf
	v_mov_b32_dpp v177, v75 row_shl:3 row_mask:0xf bank_mask:0xf
	v_mov_b32_dpp v178, v76 row_shl:3 row_mask:0xf bank_mask:0xf
	v_mov_b32_dpp v179, v77 row_shl:3 row_mask:0xf bank_mask:0xf
	v_mov_b32_dpp v176, v126 row_shl:4 row_mask:0xf bank_mask:0xf
	v_mov_b32_dpp v177, v127 row_shl:4 row_mask:0xf bank_mask:0xf
	v_mov_b32_dpp v178, v128 row_shl:4 row_mask:0xf bank_mask:0xf
	v_mov_b32_dpp v179, v129 row_shl:4 row_mask:0xf bank_mask:0xf
	v_mov_b32_dpp v176, v66 row_shl:5 row_mask:0xf bank_mask:0xf
	v_mov_b32_dpp v177, v67 row_shl:5 row_mask:0xf bank_mask:0xf
	v_mov_b32_dpp v178, v68 row_shl:5 row_mask:0xf bank_mask:0xf
	v_mov_b32_dpp v179, v69 row_shl:5 row_mask:0xf bank_mask:0xf
	v_mov_b32_dpp v176, v122 row_shl:6 row_mask:0xf bank_mask:0xf
	v_mov_b32_dpp v177, v123 row_shl:6 row_mask:0xf bank_mask:0xf
	v_mov_b32_dpp v178, v124 row_shl:6 row_mask:0xf bank_mask:0xf
	v_mov_b32_dpp v179, v125 row_shl:6 row_mask:0xf bank_mask:0xf
	v_mov_b32_dpp v176, v70 row_shl:7 row_mask:0xf bank_mask:0xf
	v_mov_b32_dpp v177, v71 row_shl:7 row_mask:0xf bank_mask:0xf
	v_mov_b32_dpp v178, v72 row_shl:7 row_mask:0xf bank_mask:0xf
	v_mov_b32_dpp v179, v73 row_shl:7 row_mask:0xf bank_mask:0xf
	v_sub_u32_e32 v184, 15, v174
	v_and_b32_e32 v182, 1, v184
	v_lshlrev_b32_e32 v182, 4, v182
	v_bfe_u32 v183, v184, 1, 1
	v_lshl_or_b32 v182, v183, 9, v182
	v_bfe_u32 v183, v184, 2, 1
	v_mul_u32_u24_e32 v183, 0xb000, v183
	v_add_u32_e32 v182, v182, v183
	v_cmp_lt_u32_e32 vcc, 7, v174
	s_and_saveexec_b64 s[0:1], vcc
	s_cbranch_execz .LBB0_101
	s_lshl_b32 s4, s10, 2
	s_or_b32 s5, s4, 2
	s_mul_hi_i32 s7, s5, 0xb000
	s_mul_i32 s5, s5, 0xb000
	v_readlane_b32 s8, v252, 43
	v_readlane_b32 s9, v252, 44
	s_nop 1
	s_add_u32 s6, s8, s5
	s_addc_u32 s7, s9, s7
	v_lshlrev_b64 v[78:79], 2, v[78:79]
	v_lshl_add_u64 v[180:181], s[6:7], 0, v[78:79]
	v_add_co_u32_e32 v180, vcc, v180, v182
	s_nop 1
	v_addc_co_u32_e32 v181, vcc, 0, v181, vcc
	global_store_dwordx4 v[180:181], v[176:179], off
